# code placement: only the D latent tile loop shifted by 4 bytes; a second pad after the loop restores the byte phase of all code behind it
# baseline (speedup 1.0000x reference)
; #define LAS __attribute__((address_space(3)))
; DI float shx(float v, int m, int lane) { return __builtin_bit_cast(float, __builtin_amdgcn_ds_bpermute((lane ^ m) << 2, __builtin_bit_cast(int, v))); }
; DI void attn_unit_d32(const Ctx& C, const bf16_t* __restrict__ Z, bf16_t* __restrict__ Y, int b, int qsel, int hsel, bool ctxq, float lam, float post_scale, const float* subln, const float mref) {
;     ...
;         for (int d = 0; d < 4; ++d)
; #pragma unroll
;             for (int kb = 0; kb < 2; ++kb)
; #pragma unroll
;                 for (int s = 0; s < 2; ++s) { const LAS bf16_t* vp = Vt + (32 * d + l31) * VST + 32 * kb + 16 * s + 4 * hh;
;                     const u32x2 lo = *(const LAS u32x2*)vp, hi = *(const LAS u32x2*)(vp + 8);
;                     u32x4 av; av.x = lo.x; av.y = lo.y; av.z = hi.x; av.w = hi.y;
;                     o[d] = __builtin_amdgcn_mfma_f32_32x32x16_bf16(__builtin_bit_cast(bf16x8, av), pf[kb][s], o[d], 0, 0, 0); }
;         __syncthreads();
;     }
;     ...
;     float l = lsum; l += shx(l, 32, lane); const float linv = 1.f / l;
;     LAS float* X = (LAS float*)C.lds + (32 * qg + l31) * 132;
;     if (sm == 1) {
; #pragma unroll
;         for (int d = 0; d < 4; ++d)
; #pragma unroll
;             for (int g = 0; g < 4; ++g) { const f32x4 v = {o[d][4 * g] * linv, o[d][4 * g + 1] * linv, o[d][4 * g + 2] * linv, o[d][4 * g + 3] * linv};
;                 *(LAS f32x4*)(X + 32 * d + 8 * g + 4 * hh) = v; }
;     }
.Ldt_plain:
	s_waitcnt lgkmcnt(7)
	v_mfma_f32_32x32x16_bf16 v[68:83], v[244:247], v[84:87], v[68:83]
	s_waitcnt lgkmcnt(6)
	v_mfma_f32_32x32x16_bf16 v[68:83], v[210:213], v[88:91], v[68:83]
	s_waitcnt lgkmcnt(5)
	v_mfma_f32_32x32x16_bf16 v[52:67], v[214:217], v[84:87], v[52:67]
	s_waitcnt lgkmcnt(4)
	v_mfma_f32_32x32x16_bf16 v[52:67], v[218:221], v[88:91], v[52:67]
	s_waitcnt lgkmcnt(3)
	v_mfma_f32_32x32x16_bf16 v[36:51], v[222:225], v[84:87], v[36:51]
	s_waitcnt lgkmcnt(2)
	v_mfma_f32_32x32x16_bf16 v[36:51], v[240:243], v[88:91], v[36:51]
	s_waitcnt lgkmcnt(1)
	v_mfma_f32_32x32x16_bf16 v[20:35], v[108:111], v[84:87], v[20:35]
	s_waitcnt lgkmcnt(0)
	s_barrier
	v_mfma_f32_32x32x16_bf16 v[20:35], v[112:115], v[88:91], v[20:35]
	v_add_f32_e32 v193, v193, v209
	s_add_i32 s22, s22, 64
	s_nop 0
	ds_bpermute_b32 v0, v186, v193
	s_waitcnt lgkmcnt(0)
	v_add_f32_e32 v0, v193, v0
	v_div_scale_f32 v84, s[0:1], v0, v0, 1.0
	v_rcp_f32_e32 v85, v84
	s_nop 0
	v_fma_f32 v86, -v84, v85, 1.0
	v_fmac_f32_e32 v85, v86, v85
	v_div_scale_f32 v86, vcc, 1.0, v0, 1.0
	v_mul_f32_e32 v87, v86, v85
	v_fma_f32 v88, -v84, v87, v86
	v_fmac_f32_e32 v87, v88, v85
	v_fma_f32 v84, -v84, v87, v86
	v_div_fmas_f32 v84, v84, v85, v87
	v_div_fixup_f32 v0, v84, v0, 1.0
	s_andn2_b64 vcc, exec, s[6:7]
	s_cbranch_vccnz .LBB0_410
	v_pk_mul_f32 v[84:85], v[68:69], v[0:1] op_sel_hi:[1,0]
	v_pk_mul_f32 v[86:87], v[70:71], v[0:1] op_sel_hi:[1,0]
	ds_write_b128 v190, v[84:87]
	v_pk_mul_f32 v[84:85], v[72:73], v[0:1] op_sel_hi:[1,0]
	v_pk_mul_f32 v[86:87], v[74:75], v[0:1] op_sel_hi:[1,0]
	ds_write_b128 v190, v[84:87] offset:32
	v_pk_mul_f32 v[84:85], v[76:77], v[0:1] op_sel_hi:[1,0]
	v_pk_mul_f32 v[86:87], v[78:79], v[0:1] op_sel_hi:[1,0]
	ds_write_b128 v190, v[84:87] offset:64
	v_pk_mul_f32 v[84:85], v[80:81], v[0:1] op_sel_hi:[1,0]
	v_pk_mul_f32 v[86:87], v[82:83], v[0:1] op_sel_hi:[1,0]
	ds_write_b128 v190, v[84:87] offset:96
	v_pk_mul_f32 v[84:85], v[52:53], v[0:1] op_sel_hi:[1,0]
	v_pk_mul_f32 v[86:87], v[54:55], v[0:1] op_sel_hi:[1,0]
	ds_write_b128 v190, v[84:87] offset:128
	v_pk_mul_f32 v[84:85], v[56:57], v[0:1] op_sel_hi:[1,0]
	v_pk_mul_f32 v[86:87], v[58:59], v[0:1] op_sel_hi:[1,0]
	ds_write_b128 v190, v[84:87] offset:160
	v_pk_mul_f32 v[84:85], v[60:61], v[0:1] op_sel_hi:[1,0]
	v_pk_mul_f32 v[86:87], v[62:63], v[0:1] op_sel_hi:[1,0]
	ds_write_b128 v190, v[84:87] offset:192
	v_pk_mul_f32 v[84:85], v[64:65], v[0:1] op_sel_hi:[1,0]
	v_pk_mul_f32 v[86:87], v[66:67], v[0:1] op_sel_hi:[1,0]
	ds_write_b128 v190, v[84:87] offset:224
	v_pk_mul_f32 v[84:85], v[36:37], v[0:1] op_sel_hi:[1,0]
	v_pk_mul_f32 v[86:87], v[38:39], v[0:1] op_sel_hi:[1,0]
	ds_write_b128 v190, v[84:87] offset:256
	v_pk_mul_f32 v[84:85], v[40:41], v[0:1] op_sel_hi:[1,0]
	v_pk_mul_f32 v[86:87], v[42:43], v[0:1] op_sel_hi:[1,0]
	ds_write_b128 v190, v[84:87] offset:288
	v_pk_mul_f32 v[84:85], v[44:45], v[0:1] op_sel_hi:[1,0]
	v_pk_mul_f32 v[86:87], v[46:47], v[0:1] op_sel_hi:[1,0]
	ds_write_b128 v190, v[84:87] offset:320
	v_pk_mul_f32 v[84:85], v[48:49], v[0:1] op_sel_hi:[1,0]
	v_pk_mul_f32 v[86:87], v[50:51], v[0:1] op_sel_hi:[1,0]
	ds_write_b128 v190, v[84:87] offset:352
	v_pk_mul_f32 v[84:85], v[20:21], v[0:1] op_sel_hi:[1,0]
	v_pk_mul_f32 v[86:87], v[22:23], v[0:1] op_sel_hi:[1,0]
	ds_write_b128 v190, v[84:87] offset:384
	v_pk_mul_f32 v[84:85], v[24:25], v[0:1] op_sel_hi:[1,0]
	v_pk_mul_f32 v[86:87], v[26:27], v[0:1] op_sel_hi:[1,0]
	ds_write_b128 v190, v[84:87] offset:416
	v_pk_mul_f32 v[84:85], v[28:29], v[0:1] op_sel_hi:[1,0]
	v_pk_mul_f32 v[86:87], v[30:31], v[0:1] op_sel_hi:[1,0]
	ds_write_b128 v190, v[84:87] offset:448
	v_pk_mul_f32 v[84:85], v[32:33], v[0:1] op_sel_hi:[1,0]
	v_pk_mul_f32 v[86:87], v[34:35], v[0:1] op_sel_hi:[1,0]
	ds_write_b128 v190, v[84:87] offset:480
